# cand G + grid barrier XCD leader: followers released (XGEN add) before the leader's own buffer_inv instead of after it (7 of 8 barrier copies)
# speedup vs baseline: 1.0030x; 1.0030x over previous
.LBB0_319:
	s_or_b64 exec, exec, s[2:3]
	s_mov_b64 s[2:3], exec
	v_mbcnt_lo_u32_b32 v0, s2, 0
	v_mbcnt_hi_u32_b32 v0, s3, v0
	s_mov_b32 s7, 0
	v_cmp_eq_u32_e32 vcc, 0, v0
	s_waitcnt vmcnt(0)
	s_and_saveexec_b64 s[4:5], vcc
	s_cbranch_execz .LBB0_321
	s_add_i32 s6, s20, 0x900
	s_lshl_b64 s[6:7], s[6:7], 2
	s_add_u32 s6, s92, s6
	s_addc_u32 s7, s93, s7
	s_bcnt1_i32_b64 s2, s[2:3]
	v_mov_b32_e32 v0, 0
	v_mov_b32_e32 v1, s2
	global_atomic_add v0, v1, s[6:7]
.LBB0_321:
	s_or_b64 exec, exec, s[4:5]
	buffer_inv sc1
	s_waitcnt vmcnt(0)

.LBB0_673:
	s_or_b64 exec, exec, s[2:3]
	s_mov_b64 s[2:3], exec
	v_mbcnt_lo_u32_b32 v0, s2, 0
	v_mbcnt_hi_u32_b32 v0, s3, v0
	v_cmp_eq_u32_e32 vcc, 0, v0
	s_waitcnt vmcnt(0)
	s_and_saveexec_b64 s[4:5], vcc
	s_cbranch_execz .LBB0_675
	s_add_i32 s66, s18, 0x900
	s_lshl_b64 s[6:7], s[66:67], 2
	s_add_u32 s6, s20, s6
	s_addc_u32 s7, s21, s7
	s_bcnt1_i32_b64 s2, s[2:3]
	v_mov_b32_e32 v0, s2
	global_atomic_add v1, v0, s[6:7]

.LBB0_996:
	s_or_b64 exec, exec, s[2:3]
	s_mov_b64 s[2:3], exec
	v_mbcnt_lo_u32_b32 v0, s2, 0
	v_mbcnt_hi_u32_b32 v0, s3, v0
	v_cmp_eq_u32_e32 vcc, 0, v0
	s_waitcnt vmcnt(0)
	s_and_saveexec_b64 s[4:5], vcc
	s_cbranch_execz .LBB0_998
	s_mov_b32 s7, s97
	s_add_i32 s6, s18, 0x900
	s_lshl_b64 s[6:7], s[6:7], 2
	s_add_u32 s6, s92, s6
	s_addc_u32 s7, s93, s7
	s_bcnt1_i32_b64 s2, s[2:3]
	v_mov_b32_e32 v0, s2
	global_atomic_add v1, v0, s[6:7]

.LBB0_1201:
	s_or_b64 exec, exec, s[2:3]
	s_mov_b64 s[2:3], exec
	v_mbcnt_lo_u32_b32 v0, s2, 0
	v_mbcnt_hi_u32_b32 v0, s3, v0
	v_cmp_eq_u32_e32 vcc, 0, v0
	s_waitcnt vmcnt(0)
	s_and_saveexec_b64 s[4:5], vcc
	s_cbranch_execz .LBB0_1203
	s_add_i32 s74, s18, 0x900
	s_lshl_b64 s[6:7], s[74:75], 2
	s_add_u32 s6, s92, s6
	s_addc_u32 s7, s93, s7
	s_bcnt1_i32_b64 s2, s[2:3]
	v_mov_b32_e32 v0, s2
	global_atomic_add v1, v0, s[6:7]
